# staging waves compute a chunk in registers/private scratch before polling the scan progress; only the shared-buffer writes, the partial-sum pass and the publish follow the poll
# speedup vs baseline: 1.0109x; 1.0100x over previous
.Lsc_G:
	v_add_u32_e32 v1, 0xffffff00, v173
	v_lshrrev_b32_e32 v2, 3, v1
	v_and_b32_e32 v3, 7, v1
	s_and_b32 s8, s4, 7
	s_bfe_u32 s10, s4, 0x20003
	s_lshr_b32 s11, s4, 7
	s_bfe_u32 s9, s4, 0x20005
	s_lshl_b32 s9, s9, 13
	v_readlane_b32 s50, v242, 0
	v_readlane_b32 s51, v242, 1
	v_readlane_b32 s16, v242, 62
	s_load_dwordx4 s[12:15], s[50:51], 0x68
	s_add_u32 s36, s90, 0x5e00000
	s_addc_u32 s37, s91, 0
	s_add_u32 s38, s90, 0x7e00000
	s_addc_u32 s39, s91, 0
	s_add_u32 s44, s90, 0x9e00000
	s_addc_u32 s45, s91, 0
	s_add_u32 s46, s90, 0x1c00000
	s_addc_u32 s47, s91, 0
	s_lshl_b32 s68, s11, 25
	s_add_u32 s69, s68, 0x13e00000
	s_add_u32 s40, s90, s69
	s_addc_u32 s41, s91, 0
	s_add_u32 s69, s68, 0x17e00000
	s_add_u32 s42, s90, s69
	s_addc_u32 s43, s91, 0
	s_lshl_b32 s68, s11, 26
	s_add_u32 s68, s68, 0xbe00000
	s_add_u32 s48, s90, s68
	s_addc_u32 s49, s91, 0
	s_cmp_eq_u32 s11, 0
	s_mov_b32 s54, 0x8000
	s_movk_i32 s55, 0x400
	s_mov_b32 s64, 0x10000
	s_cselect_b32 s54, s54, 0xffff8000
	s_cselect_b32 s55, s55, 0xfffffc00
	s_cselect_b32 s64, s64, 0xffff0000
	s_cselect_b64 vcc, -1, 0
	v_sub_u32_e32 v4, 0x1fff, v2
	s_nop 3
	v_cndmask_b32_e32 v4, v4, v2, vcc
	v_add_u32_e32 v4, s9, v4
	s_lshl_b32 s68, s8, 7
	v_lshlrev_b32_e32 v5, 10, v4
	v_lshl_add_u32 v5, v3, 3, v5
	v_add_u32_e32 v5, s68, v5
	s_lshl_b32 s69, s8, 2
	v_lshlrev_b32_e32 v6, 5, v4
	v_add_u32_e32 v6, s69, v6
	s_lshl_b32 s69, s10, 5
	s_add_i32 s69, s69, s68
	v_lshlrev_b32_e32 v9, 10, v4
	v_lshl_add_u32 v9, v3, 2, v9
	v_add_u32_e32 v9, s69, v9
	s_lshl_b32 s69, s69, 1
	v_lshlrev_b32_e32 v7, 11, v4
	v_lshl_add_u32 v7, v3, 3, v7
	v_add_u32_e32 v7, s69, v7
	v_mul_u32_u24_e32 v8, 1024, v2
	v_lshl_add_u32 v8, v3, 4, v8
	v_add_u32_e32 v138, 512, v8
	v_add_u32_e32 v140, 35328, v8
	v_add_u32_e32 v152, -4, v0
	v_lshlrev_b32_e32 v152, 13, v152
	v_add_u32_e32 v152, 107072, v152
	v_and_b32_e32 v156, 7, v2
	v_lshlrev_b32_e32 v153, 8, v156
	v_lshl_add_u32 v153, v3, 4, v153
	v_add_u32_e32 v153, v152, v153
	v_and_b32_e32 v154, 63, v1
	v_lshl_add_u32 v154, v154, 2, v152
	v_add_u32_e32 v155, 2048, v154
	v_add_u32_e32 v139, -1, v2
	v_mul_u32_u24_e32 v139, 1024, v139
	v_lshl_add_u32 v139, v3, 4, v139
	v_add_u32_e32 v141, 35328, v139
	v_add_u32_e32 v139, 512, v139
	v_cmp_eq_u32_e32 vcc, 0, v2
	s_nop 1
	v_cndmask_b32_e32 v139, v139, v152, vcc
	v_cndmask_b32_e32 v141, v141, v152, vcc
	v_lshrrev_b32_e32 v158, 3, v2
	v_lshlrev_b32_e32 v158, 8, v158
	v_lshl_add_u32 v158, v3, 4, v158
	v_and_b32_e32 v159, 63, v1
	v_lshlrev_b32_e32 v159, 2, v159
	v_add_u32_e32 v106, -4, v0
	v_lshl_add_u32 v159, v106, 8, v159
	v_add_u32_e32 v159, 33792, v159
	v_mov_b32_e32 v106, 1.0
	ds_write_b32 v155, v106
	v_add_u32_e32 v158, 32768, v158
	v_mul_u32_u24_e32 v142, 288, v3
	v_lshl_add_u32 v142, v2, 2, v142
	v_add_u32_e32 v143, 71936, v142
	v_add_u32_e32 v142, 69632, v142
	v_lshlrev_b32_e32 v11, 9, v2
	v_lshl_add_u32 v11, v3, 6, v11
	v_add_u32_e32 v11, 74240, v11
	s_lshl_b32 s69, s8, 6
	s_add_i32 s69, s69, s16
	v_lshl_add_u32 v106, v3, 2, s69
	v_lshlrev_b32_e32 v106, 2, v106
	s_waitcnt lgkmcnt(0)
	global_load_dwordx4 v[12:15], v106, s[12:13]
	global_load_dwordx4 v[16:19], v106, s[12:13] offset:128
	global_load_dwordx4 v[20:23], v106, s[14:15]
	global_load_dwordx4 v[24:27], v106, s[14:15] offset:128
	global_load_dwordx2 v[28:29], v5, s[36:37]
	global_load_dwordx2 v[30:31], v5, s[36:37] offset:64
	global_load_dwordx2 v[32:33], v5, s[38:39]
	global_load_dwordx2 v[34:35], v5, s[38:39] offset:64
	global_load_dwordx2 v[36:37], v5, s[40:41]
	global_load_dwordx2 v[38:39], v5, s[40:41] offset:64
	global_load_dwordx2 v[40:41], v5, s[42:43]
	global_load_dwordx2 v[42:43], v5, s[42:43] offset:64
	global_load_dword v44, v6, s[46:47]
	global_load_dword v45, v9, s[44:45]
	v_add_u32_e32 v5, s54, v5
	v_add_u32_e32 v6, s55, v6
	v_add_u32_e32 v9, s54, v9
	global_load_dwordx2 v[46:47], v5, s[36:37]
	global_load_dwordx2 v[48:49], v5, s[36:37] offset:64
	global_load_dwordx2 v[50:51], v5, s[38:39]
	global_load_dwordx2 v[52:53], v5, s[38:39] offset:64
	global_load_dwordx2 v[54:55], v5, s[40:41]
	global_load_dwordx2 v[56:57], v5, s[40:41] offset:64
	global_load_dwordx2 v[58:59], v5, s[42:43]
	global_load_dwordx2 v[60:61], v5, s[42:43] offset:64
	global_load_dword v62, v6, s[46:47]
	global_load_dword v63, v9, s[44:45]
	v_add_u32_e32 v5, s54, v5
	v_add_u32_e32 v6, s55, v6
	v_add_u32_e32 v9, s54, v9
	v_cmp_eq_u32_e64 s[12:13], 0, v156
	v_cmp_eq_u32_e64 s[14:15], 7, v156
	s_mov_b32 s6, 0
	v_mov_b32_e32 v144, 107024
	v_mov_b32_e32 v145, v164
	v_mov_b32_e32 v146, 0
	s_waitcnt vmcnt(10)
	v_lshlrev_b32_e32 v64, 16, v36
	v_and_b32_e32 v65, 0xffff0000, v36
	v_mul_f32_e32 v64, 0x3fb8aa3b, v64
	v_mul_f32_e32 v65, 0x3fb8aa3b, v65
	v_lshlrev_b32_e32 v66, 16, v37
	v_and_b32_e32 v67, 0xffff0000, v37
	v_mul_f32_e32 v66, 0x3fb8aa3b, v66
	v_mul_f32_e32 v67, 0x3fb8aa3b, v67
	v_lshlrev_b32_e32 v68, 16, v38
	v_and_b32_e32 v69, 0xffff0000, v38
	v_mul_f32_e32 v68, 0x3fb8aa3b, v68
	v_mul_f32_e32 v69, 0x3fb8aa3b, v69
	v_lshlrev_b32_e32 v70, 16, v39
	v_and_b32_e32 v71, 0xffff0000, v39
	v_mul_f32_e32 v70, 0x3fb8aa3b, v70
	v_mul_f32_e32 v71, 0x3fb8aa3b, v71
	ds_write_b128 v153, v[64:67]
	ds_write_b128 v153, v[68:71] offset:128
	s_waitcnt lgkmcnt(0)
	ds_read_b32 v124, v154 offset:0
	ds_read_b32 v125, v154 offset:256
	ds_read_b32 v126, v154 offset:512
	ds_read_b32 v127, v154 offset:768
	ds_read_b32 v128, v154 offset:1024
	ds_read_b32 v129, v154 offset:1280
	ds_read_b32 v130, v154 offset:1536
	ds_read_b32 v131, v154 offset:1792
	v_lshlrev_b32_e32 v108, 16, v32
	v_and_b32_e32 v109, 0xffff0000, v32
	v_lshlrev_b32_e32 v110, 16, v40
	v_and_b32_e32 v111, 0xffff0000, v40
	v_lshlrev_b32_e32 v96, 16, v28
	v_and_b32_e32 v97, 0xffff0000, v28
	v_pk_add_f32 v[112:113], v[110:111], -1.0 op_sel_hi:[1,0]
	v_pk_mul_f32 v[114:115], v[12:13], v[108:109]
	v_pk_fma_f32 v[112:113], v[20:21], v[112:113], 1.0 op_sel_hi:[1,1,0]
	v_pk_mul_f32 v[88:89], v[44:45], v[114:115] op_sel_hi:[0,1]
	v_pk_mul_f32 v[72:73], v[112:113], v[108:109]
	v_pk_mul_f32 v[80:81], v[88:89], v[110:111]
	v_lshlrev_b32_e32 v108, 16, v33
	v_and_b32_e32 v109, 0xffff0000, v33
	v_lshlrev_b32_e32 v110, 16, v41
	v_and_b32_e32 v111, 0xffff0000, v41
	v_lshlrev_b32_e32 v98, 16, v29
	v_and_b32_e32 v99, 0xffff0000, v29
	v_pk_add_f32 v[112:113], v[110:111], -1.0 op_sel_hi:[1,0]
	v_pk_mul_f32 v[114:115], v[14:15], v[108:109]
	v_pk_fma_f32 v[112:113], v[22:23], v[112:113], 1.0 op_sel_hi:[1,1,0]
	v_pk_mul_f32 v[90:91], v[44:45], v[114:115] op_sel_hi:[0,1]
	v_pk_mul_f32 v[74:75], v[112:113], v[108:109]
	v_pk_mul_f32 v[82:83], v[90:91], v[110:111]
	v_lshlrev_b32_e32 v108, 16, v34
	v_and_b32_e32 v109, 0xffff0000, v34
	v_lshlrev_b32_e32 v110, 16, v42
	v_and_b32_e32 v111, 0xffff0000, v42
	v_lshlrev_b32_e32 v100, 16, v30
	v_and_b32_e32 v101, 0xffff0000, v30
	v_pk_add_f32 v[112:113], v[110:111], -1.0 op_sel_hi:[1,0]
	v_pk_mul_f32 v[114:115], v[16:17], v[108:109]
	v_pk_fma_f32 v[112:113], v[24:25], v[112:113], 1.0 op_sel_hi:[1,1,0]
	v_pk_mul_f32 v[92:93], v[44:45], v[114:115] op_sel_hi:[0,1]
	v_pk_mul_f32 v[76:77], v[112:113], v[108:109]
	v_pk_mul_f32 v[84:85], v[92:93], v[110:111]
	v_lshlrev_b32_e32 v108, 16, v35
	v_and_b32_e32 v109, 0xffff0000, v35
	v_lshlrev_b32_e32 v110, 16, v43
	v_and_b32_e32 v111, 0xffff0000, v43
	v_lshlrev_b32_e32 v102, 16, v31
	v_and_b32_e32 v103, 0xffff0000, v31
	v_pk_add_f32 v[112:113], v[110:111], -1.0 op_sel_hi:[1,0]
	v_pk_mul_f32 v[114:115], v[18:19], v[108:109]
	v_pk_fma_f32 v[112:113], v[26:27], v[112:113], 1.0 op_sel_hi:[1,1,0]
	v_pk_mul_f32 v[94:95], v[44:45], v[114:115] op_sel_hi:[0,1]
	v_pk_mul_f32 v[78:79], v[112:113], v[108:109]
	v_pk_mul_f32 v[86:87], v[94:95], v[110:111]
	v_lshlrev_b32_e32 v104, 16, v45
	v_and_b32_e32 v105, 0xffff0000, v45
	s_waitcnt lgkmcnt(0)
	v_add_f32_e32 v125, v124, v125
	v_add_f32_e32 v126, v125, v126
	v_add_f32_e32 v127, v126, v127
	v_add_f32_e32 v128, v127, v128
	v_add_f32_e32 v129, v128, v129
	v_add_f32_e32 v130, v129, v130
	v_add_f32_e32 v131, v130, v131
	v_exp_f32_e64 v124, -v124
	v_exp_f32_e64 v125, -v125
	v_exp_f32_e64 v126, -v126
	v_exp_f32_e64 v127, -v127
	v_exp_f32_e64 v128, -v128
	v_exp_f32_e64 v129, -v129
	v_exp_f32_e64 v130, -v130
	v_exp_f32_e64 v131, -v131
	s_nop 0
	ds_write_b32 v155, v124 offset:256
	ds_write_b32 v155, v125 offset:512
	ds_write_b32 v155, v126 offset:768
	ds_write_b32 v155, v127 offset:1024
	ds_write_b32 v155, v128 offset:1280
	ds_write_b32 v155, v129 offset:1536
	ds_write_b32 v155, v130 offset:1792
	ds_write_b32 v155, v131 offset:2048
	v_mov_b32_e32 v161, v131
	s_waitcnt lgkmcnt(0)
	ds_read_b128 v[64:67], v153 offset:2048
	ds_read_b128 v[68:71], v153 offset:2176
	ds_read_b128 v[116:119], v153 offset:2304
	ds_read_b128 v[120:123], v153 offset:2432
	s_waitcnt lgkmcnt(0)
	v_rcp_f32_e32 v124, v116
	v_rcp_f32_e32 v125, v117
	v_rcp_f32_e32 v126, v118
	v_rcp_f32_e32 v127, v119
	v_rcp_f32_e32 v128, v120
	v_rcp_f32_e32 v129, v121
	v_rcp_f32_e32 v130, v122
	v_rcp_f32_e32 v131, v123
	s_nop 1
	v_pk_mul_f32 v[72:73], v[72:73], v[124:125]
	v_pk_mul_f32 v[80:81], v[80:81], v[124:125]
	v_pk_mul_f32 v[88:89], v[88:89], v[64:65]
	v_pk_mul_f32 v[96:97], v[96:97], v[116:117]
	v_pk_mul_f32 v[74:75], v[74:75], v[126:127]
	v_pk_mul_f32 v[82:83], v[82:83], v[126:127]
	v_pk_mul_f32 v[90:91], v[90:91], v[66:67]
	v_pk_mul_f32 v[98:99], v[98:99], v[118:119]
	v_pk_mul_f32 v[76:77], v[76:77], v[128:129]
	v_pk_mul_f32 v[84:85], v[84:85], v[128:129]
	v_pk_mul_f32 v[92:93], v[92:93], v[68:69]
	v_pk_mul_f32 v[100:101], v[100:101], v[120:121]
	v_pk_mul_f32 v[78:79], v[78:79], v[130:131]
	v_pk_mul_f32 v[86:87], v[86:87], v[130:131]
	v_pk_mul_f32 v[94:95], v[94:95], v[70:71]
	v_pk_mul_f32 v[102:103], v[102:103], v[122:123]
	global_load_dwordx2 v[28:29], v5, s[36:37]
	global_load_dwordx2 v[30:31], v5, s[36:37] offset:64
	global_load_dwordx2 v[32:33], v5, s[38:39]
	global_load_dwordx2 v[34:35], v5, s[38:39] offset:64
	global_load_dwordx2 v[36:37], v5, s[40:41]
	global_load_dwordx2 v[38:39], v5, s[40:41] offset:64
	global_load_dwordx2 v[40:41], v5, s[42:43]
	global_load_dwordx2 v[42:43], v5, s[42:43] offset:64
	global_load_dword v44, v6, s[46:47]
	global_load_dword v45, v9, s[44:45]
	v_add_u32_e32 v5, s54, v5
	v_add_u32_e32 v6, s55, v6
	v_add_u32_e32 v9, s54, v9
	ds_write_b32 v159, v161 offset:0
	ds_write_b128 v8, v[72:75] offset:0
	ds_write_b128 v8, v[76:79] offset:128
	ds_write_b128 v8, v[80:83] offset:256
	ds_write_b128 v8, v[84:87] offset:384
	ds_write2_b32 v138, v96, v97 offset0:1 offset1:3
	ds_write2_b32 v139, v88, v89 offset0:0 offset1:2
	ds_write2_b32 v138, v98, v99 offset0:65 offset1:67
	ds_write2_b32 v139, v90, v91 offset0:64 offset1:66
	ds_write2_b32 v138, v100, v101 offset0:33 offset1:35
	ds_write2_b32 v139, v92, v93 offset0:32 offset1:34
	ds_write2_b32 v138, v102, v103 offset0:97 offset1:99
	ds_write2_b32 v139, v94, v95 offset0:96 offset1:98
	ds_write2_b32 v142, v104, v105 offset1:36
	s_and_saveexec_b64 s[68:69], s[12:13]
	ds_write_b128 v158, v[88:91] offset:0
	ds_write_b128 v158, v[92:95] offset:128
	s_mov_b64 exec, s[68:69]
	s_add_i32 s6, s6, 1
	v_add_u32_e32 v146, 1, v146
	s_waitcnt lgkmcnt(0)
	ds_write_b32 v145, v146
	s_waitcnt vmcnt(10)
	v_lshlrev_b32_e32 v64, 16, v54
	v_and_b32_e32 v65, 0xffff0000, v54
	v_mul_f32_e32 v64, 0x3fb8aa3b, v64
	v_mul_f32_e32 v65, 0x3fb8aa3b, v65
	v_lshlrev_b32_e32 v66, 16, v55
	v_and_b32_e32 v67, 0xffff0000, v55
	v_mul_f32_e32 v66, 0x3fb8aa3b, v66
	v_mul_f32_e32 v67, 0x3fb8aa3b, v67
	v_lshlrev_b32_e32 v68, 16, v56
	v_and_b32_e32 v69, 0xffff0000, v56
	v_mul_f32_e32 v68, 0x3fb8aa3b, v68
	v_mul_f32_e32 v69, 0x3fb8aa3b, v69
	v_lshlrev_b32_e32 v70, 16, v57
	v_and_b32_e32 v71, 0xffff0000, v57
	v_mul_f32_e32 v70, 0x3fb8aa3b, v70
	v_mul_f32_e32 v71, 0x3fb8aa3b, v71
	ds_write_b128 v153, v[64:67]
	ds_write_b128 v153, v[68:71] offset:128
	s_waitcnt lgkmcnt(0)
	ds_read_b32 v124, v154 offset:0
	ds_read_b32 v125, v154 offset:256
	ds_read_b32 v126, v154 offset:512
	ds_read_b32 v127, v154 offset:768
	ds_read_b32 v128, v154 offset:1024
	ds_read_b32 v129, v154 offset:1280
	ds_read_b32 v130, v154 offset:1536
	ds_read_b32 v131, v154 offset:1792
	v_lshlrev_b32_e32 v108, 16, v50
	v_and_b32_e32 v109, 0xffff0000, v50
	v_lshlrev_b32_e32 v110, 16, v58
	v_and_b32_e32 v111, 0xffff0000, v58
	v_lshlrev_b32_e32 v96, 16, v46
	v_and_b32_e32 v97, 0xffff0000, v46
	v_pk_add_f32 v[112:113], v[110:111], -1.0 op_sel_hi:[1,0]
	v_pk_mul_f32 v[114:115], v[12:13], v[108:109]
	v_pk_fma_f32 v[112:113], v[20:21], v[112:113], 1.0 op_sel_hi:[1,1,0]
	v_pk_mul_f32 v[88:89], v[62:63], v[114:115] op_sel_hi:[0,1]
	v_pk_mul_f32 v[72:73], v[112:113], v[108:109]
	v_pk_mul_f32 v[80:81], v[88:89], v[110:111]
	v_lshlrev_b32_e32 v108, 16, v51
	v_and_b32_e32 v109, 0xffff0000, v51
	v_lshlrev_b32_e32 v110, 16, v59
	v_and_b32_e32 v111, 0xffff0000, v59
	v_lshlrev_b32_e32 v98, 16, v47
	v_and_b32_e32 v99, 0xffff0000, v47
	v_pk_add_f32 v[112:113], v[110:111], -1.0 op_sel_hi:[1,0]
	v_pk_mul_f32 v[114:115], v[14:15], v[108:109]
	v_pk_fma_f32 v[112:113], v[22:23], v[112:113], 1.0 op_sel_hi:[1,1,0]
	v_pk_mul_f32 v[90:91], v[62:63], v[114:115] op_sel_hi:[0,1]
	v_pk_mul_f32 v[74:75], v[112:113], v[108:109]
	v_pk_mul_f32 v[82:83], v[90:91], v[110:111]
	v_lshlrev_b32_e32 v108, 16, v52
	v_and_b32_e32 v109, 0xffff0000, v52
	v_lshlrev_b32_e32 v110, 16, v60
	v_and_b32_e32 v111, 0xffff0000, v60
	v_lshlrev_b32_e32 v100, 16, v48
	v_and_b32_e32 v101, 0xffff0000, v48
	v_pk_add_f32 v[112:113], v[110:111], -1.0 op_sel_hi:[1,0]
	v_pk_mul_f32 v[114:115], v[16:17], v[108:109]
	v_pk_fma_f32 v[112:113], v[24:25], v[112:113], 1.0 op_sel_hi:[1,1,0]
	v_pk_mul_f32 v[92:93], v[62:63], v[114:115] op_sel_hi:[0,1]
	v_pk_mul_f32 v[76:77], v[112:113], v[108:109]
	v_pk_mul_f32 v[84:85], v[92:93], v[110:111]
	v_lshlrev_b32_e32 v108, 16, v53
	v_and_b32_e32 v109, 0xffff0000, v53
	v_lshlrev_b32_e32 v110, 16, v61
	v_and_b32_e32 v111, 0xffff0000, v61
	v_lshlrev_b32_e32 v102, 16, v49
	v_and_b32_e32 v103, 0xffff0000, v49
	v_pk_add_f32 v[112:113], v[110:111], -1.0 op_sel_hi:[1,0]
	v_pk_mul_f32 v[114:115], v[18:19], v[108:109]
	v_pk_fma_f32 v[112:113], v[26:27], v[112:113], 1.0 op_sel_hi:[1,1,0]
	v_pk_mul_f32 v[94:95], v[62:63], v[114:115] op_sel_hi:[0,1]
	v_pk_mul_f32 v[78:79], v[112:113], v[108:109]
	v_pk_mul_f32 v[86:87], v[94:95], v[110:111]
	v_lshlrev_b32_e32 v104, 16, v63
	v_and_b32_e32 v105, 0xffff0000, v63
	s_waitcnt lgkmcnt(0)
	v_add_f32_e32 v125, v124, v125
	v_add_f32_e32 v126, v125, v126
	v_add_f32_e32 v127, v126, v127
	v_add_f32_e32 v128, v127, v128
	v_add_f32_e32 v129, v128, v129
	v_add_f32_e32 v130, v129, v130
	v_add_f32_e32 v131, v130, v131
	v_exp_f32_e64 v124, -v124
	v_exp_f32_e64 v125, -v125
	v_exp_f32_e64 v126, -v126
	v_exp_f32_e64 v127, -v127
	v_exp_f32_e64 v128, -v128
	v_exp_f32_e64 v129, -v129
	v_exp_f32_e64 v130, -v130
	v_exp_f32_e64 v131, -v131
	s_nop 0
	ds_write_b32 v155, v124 offset:256
	ds_write_b32 v155, v125 offset:512
	ds_write_b32 v155, v126 offset:768
	ds_write_b32 v155, v127 offset:1024
	ds_write_b32 v155, v128 offset:1280
	ds_write_b32 v155, v129 offset:1536
	ds_write_b32 v155, v130 offset:1792
	ds_write_b32 v155, v131 offset:2048
	v_mov_b32_e32 v161, v131
	s_waitcnt lgkmcnt(0)
	ds_read_b128 v[64:67], v153 offset:2048
	ds_read_b128 v[68:71], v153 offset:2176
	ds_read_b128 v[116:119], v153 offset:2304
	ds_read_b128 v[120:123], v153 offset:2432
	s_waitcnt lgkmcnt(0)
	v_rcp_f32_e32 v124, v116
	v_rcp_f32_e32 v125, v117
	v_rcp_f32_e32 v126, v118
	v_rcp_f32_e32 v127, v119
	v_rcp_f32_e32 v128, v120
	v_rcp_f32_e32 v129, v121
	v_rcp_f32_e32 v130, v122
	v_rcp_f32_e32 v131, v123
	s_nop 1
	v_pk_mul_f32 v[72:73], v[72:73], v[124:125]
	v_pk_mul_f32 v[80:81], v[80:81], v[124:125]
	v_pk_mul_f32 v[88:89], v[88:89], v[64:65]
	v_pk_mul_f32 v[96:97], v[96:97], v[116:117]
	v_pk_mul_f32 v[74:75], v[74:75], v[126:127]
	v_pk_mul_f32 v[82:83], v[82:83], v[126:127]
	v_pk_mul_f32 v[90:91], v[90:91], v[66:67]
	v_pk_mul_f32 v[98:99], v[98:99], v[118:119]
	v_pk_mul_f32 v[76:77], v[76:77], v[128:129]
	v_pk_mul_f32 v[84:85], v[84:85], v[128:129]
	v_pk_mul_f32 v[92:93], v[92:93], v[68:69]
	v_pk_mul_f32 v[100:101], v[100:101], v[120:121]
	v_pk_mul_f32 v[78:79], v[78:79], v[130:131]
	v_pk_mul_f32 v[86:87], v[86:87], v[130:131]
	v_pk_mul_f32 v[94:95], v[94:95], v[70:71]
	v_pk_mul_f32 v[102:103], v[102:103], v[122:123]
	global_load_dwordx2 v[46:47], v5, s[36:37]
	global_load_dwordx2 v[48:49], v5, s[36:37] offset:64
	global_load_dwordx2 v[50:51], v5, s[38:39]
	global_load_dwordx2 v[52:53], v5, s[38:39] offset:64
	global_load_dwordx2 v[54:55], v5, s[40:41]
	global_load_dwordx2 v[56:57], v5, s[40:41] offset:64
	global_load_dwordx2 v[58:59], v5, s[42:43]
	global_load_dwordx2 v[60:61], v5, s[42:43] offset:64
	global_load_dword v62, v6, s[46:47]
	global_load_dword v63, v9, s[44:45]
	v_add_u32_e32 v5, s54, v5
	v_add_u32_e32 v6, s55, v6
	v_add_u32_e32 v9, s54, v9
	ds_write_b32 v159, v161 offset:34816
	ds_write_b128 v8, v[72:75] offset:34816
	ds_write_b128 v8, v[76:79] offset:34944
	ds_write_b128 v8, v[80:83] offset:35072
	ds_write_b128 v8, v[84:87] offset:35200
	ds_write2_b32 v140, v96, v97 offset0:1 offset1:3
	ds_write2_b32 v141, v88, v89 offset0:0 offset1:2
	ds_write2_b32 v140, v98, v99 offset0:65 offset1:67
	ds_write2_b32 v141, v90, v91 offset0:64 offset1:66
	ds_write2_b32 v140, v100, v101 offset0:33 offset1:35
	ds_write2_b32 v141, v92, v93 offset0:32 offset1:34
	ds_write2_b32 v140, v102, v103 offset0:97 offset1:99
	ds_write2_b32 v141, v94, v95 offset0:96 offset1:98
	ds_write2_b32 v143, v104, v105 offset1:36
	s_and_saveexec_b64 s[68:69], s[12:13]
	ds_write_b128 v158, v[88:91] offset:34816
	ds_write_b128 v158, v[92:95] offset:34944
	s_mov_b64 exec, s[68:69]
	s_add_i32 s6, s6, 1
	v_add_u32_e32 v146, 1, v146
	s_waitcnt lgkmcnt(0)
	ds_write_b32 v145, v146
.Lsc_G_loop:
	s_waitcnt vmcnt(10)
	v_lshlrev_b32_e32 v64, 16, v36
	v_and_b32_e32 v65, 0xffff0000, v36
	v_mul_f32_e32 v64, 0x3fb8aa3b, v64
	v_mul_f32_e32 v65, 0x3fb8aa3b, v65
	v_lshlrev_b32_e32 v66, 16, v37
	v_and_b32_e32 v67, 0xffff0000, v37
	v_mul_f32_e32 v66, 0x3fb8aa3b, v66
	v_mul_f32_e32 v67, 0x3fb8aa3b, v67
	v_lshlrev_b32_e32 v68, 16, v38
	v_and_b32_e32 v69, 0xffff0000, v38
	v_mul_f32_e32 v68, 0x3fb8aa3b, v68
	v_mul_f32_e32 v69, 0x3fb8aa3b, v69
	v_lshlrev_b32_e32 v70, 16, v39
	v_and_b32_e32 v71, 0xffff0000, v39
	v_mul_f32_e32 v70, 0x3fb8aa3b, v70
	v_mul_f32_e32 v71, 0x3fb8aa3b, v71
	ds_write_b128 v153, v[64:67]
	ds_write_b128 v153, v[68:71] offset:128
	s_waitcnt lgkmcnt(0)
	ds_read_b32 v124, v154 offset:0
	ds_read_b32 v125, v154 offset:256
	ds_read_b32 v126, v154 offset:512
	ds_read_b32 v127, v154 offset:768
	ds_read_b32 v128, v154 offset:1024
	ds_read_b32 v129, v154 offset:1280
	ds_read_b32 v130, v154 offset:1536
	ds_read_b32 v131, v154 offset:1792
	v_lshlrev_b32_e32 v108, 16, v32
	v_and_b32_e32 v109, 0xffff0000, v32
	v_lshlrev_b32_e32 v110, 16, v40
	v_and_b32_e32 v111, 0xffff0000, v40
	v_lshlrev_b32_e32 v96, 16, v28
	v_and_b32_e32 v97, 0xffff0000, v28
	v_pk_add_f32 v[112:113], v[110:111], -1.0 op_sel_hi:[1,0]
	v_pk_mul_f32 v[114:115], v[12:13], v[108:109]
	v_pk_fma_f32 v[112:113], v[20:21], v[112:113], 1.0 op_sel_hi:[1,1,0]
	v_pk_mul_f32 v[88:89], v[44:45], v[114:115] op_sel_hi:[0,1]
	v_pk_mul_f32 v[72:73], v[112:113], v[108:109]
	v_pk_mul_f32 v[80:81], v[88:89], v[110:111]
	v_lshlrev_b32_e32 v108, 16, v33
	v_and_b32_e32 v109, 0xffff0000, v33
	v_lshlrev_b32_e32 v110, 16, v41
	v_and_b32_e32 v111, 0xffff0000, v41
	v_lshlrev_b32_e32 v98, 16, v29
	v_and_b32_e32 v99, 0xffff0000, v29
	v_pk_add_f32 v[112:113], v[110:111], -1.0 op_sel_hi:[1,0]
	v_pk_mul_f32 v[114:115], v[14:15], v[108:109]
	v_pk_fma_f32 v[112:113], v[22:23], v[112:113], 1.0 op_sel_hi:[1,1,0]
	v_pk_mul_f32 v[90:91], v[44:45], v[114:115] op_sel_hi:[0,1]
	v_pk_mul_f32 v[74:75], v[112:113], v[108:109]
	v_pk_mul_f32 v[82:83], v[90:91], v[110:111]
	v_lshlrev_b32_e32 v108, 16, v34
	v_and_b32_e32 v109, 0xffff0000, v34
	v_lshlrev_b32_e32 v110, 16, v42
	v_and_b32_e32 v111, 0xffff0000, v42
	v_lshlrev_b32_e32 v100, 16, v30
	v_and_b32_e32 v101, 0xffff0000, v30
	v_pk_add_f32 v[112:113], v[110:111], -1.0 op_sel_hi:[1,0]
	v_pk_mul_f32 v[114:115], v[16:17], v[108:109]
	v_pk_fma_f32 v[112:113], v[24:25], v[112:113], 1.0 op_sel_hi:[1,1,0]
	v_pk_mul_f32 v[92:93], v[44:45], v[114:115] op_sel_hi:[0,1]
	v_pk_mul_f32 v[76:77], v[112:113], v[108:109]
	v_pk_mul_f32 v[84:85], v[92:93], v[110:111]
	v_lshlrev_b32_e32 v108, 16, v35
	v_and_b32_e32 v109, 0xffff0000, v35
	v_lshlrev_b32_e32 v110, 16, v43
	v_and_b32_e32 v111, 0xffff0000, v43
	v_lshlrev_b32_e32 v102, 16, v31
	v_and_b32_e32 v103, 0xffff0000, v31
	v_pk_add_f32 v[112:113], v[110:111], -1.0 op_sel_hi:[1,0]
	v_pk_mul_f32 v[114:115], v[18:19], v[108:109]
	v_pk_fma_f32 v[112:113], v[26:27], v[112:113], 1.0 op_sel_hi:[1,1,0]
	v_pk_mul_f32 v[94:95], v[44:45], v[114:115] op_sel_hi:[0,1]
	v_pk_mul_f32 v[78:79], v[112:113], v[108:109]
	v_pk_mul_f32 v[86:87], v[94:95], v[110:111]
	v_lshlrev_b32_e32 v104, 16, v45
	v_and_b32_e32 v105, 0xffff0000, v45
	s_waitcnt lgkmcnt(0)
	v_add_f32_e32 v125, v124, v125
	v_add_f32_e32 v126, v125, v126
	v_add_f32_e32 v127, v126, v127
	v_add_f32_e32 v128, v127, v128
	v_add_f32_e32 v129, v128, v129
	v_add_f32_e32 v130, v129, v130
	v_add_f32_e32 v131, v130, v131
	v_exp_f32_e64 v124, -v124
	v_exp_f32_e64 v125, -v125
	v_exp_f32_e64 v126, -v126
	v_exp_f32_e64 v127, -v127
	v_exp_f32_e64 v128, -v128
	v_exp_f32_e64 v129, -v129
	v_exp_f32_e64 v130, -v130
	v_exp_f32_e64 v131, -v131
	s_nop 0
	ds_write_b32 v155, v124 offset:256
	ds_write_b32 v155, v125 offset:512
	ds_write_b32 v155, v126 offset:768
	ds_write_b32 v155, v127 offset:1024
	ds_write_b32 v155, v128 offset:1280
	ds_write_b32 v155, v129 offset:1536
	ds_write_b32 v155, v130 offset:1792
	ds_write_b32 v155, v131 offset:2048
	v_mov_b32_e32 v161, v131
	s_waitcnt lgkmcnt(0)
	ds_read_b128 v[64:67], v153 offset:2048
	ds_read_b128 v[68:71], v153 offset:2176
	ds_read_b128 v[116:119], v153 offset:2304
	ds_read_b128 v[120:123], v153 offset:2432
	s_waitcnt lgkmcnt(0)
	v_rcp_f32_e32 v124, v116
	v_rcp_f32_e32 v125, v117
	v_rcp_f32_e32 v126, v118
	v_rcp_f32_e32 v127, v119
	v_rcp_f32_e32 v128, v120
	v_rcp_f32_e32 v129, v121
	v_rcp_f32_e32 v130, v122
	v_rcp_f32_e32 v131, v123
	s_nop 1
	v_pk_mul_f32 v[72:73], v[72:73], v[124:125]
	v_pk_mul_f32 v[80:81], v[80:81], v[124:125]
	v_pk_mul_f32 v[88:89], v[88:89], v[64:65]
	v_pk_mul_f32 v[96:97], v[96:97], v[116:117]
	v_pk_mul_f32 v[74:75], v[74:75], v[126:127]
	v_pk_mul_f32 v[82:83], v[82:83], v[126:127]
	v_pk_mul_f32 v[90:91], v[90:91], v[66:67]
	v_pk_mul_f32 v[98:99], v[98:99], v[118:119]
	v_pk_mul_f32 v[76:77], v[76:77], v[128:129]
	v_pk_mul_f32 v[84:85], v[84:85], v[128:129]
	v_pk_mul_f32 v[92:93], v[92:93], v[68:69]
	v_pk_mul_f32 v[100:101], v[100:101], v[120:121]
	v_pk_mul_f32 v[78:79], v[78:79], v[130:131]
	v_pk_mul_f32 v[86:87], v[86:87], v[130:131]
	v_pk_mul_f32 v[94:95], v[94:95], v[70:71]
	v_pk_mul_f32 v[102:103], v[102:103], v[122:123]
	global_load_dwordx2 v[28:29], v5, s[36:37]
	global_load_dwordx2 v[30:31], v5, s[36:37] offset:64
	global_load_dwordx2 v[32:33], v5, s[38:39]
	global_load_dwordx2 v[34:35], v5, s[38:39] offset:64
	global_load_dwordx2 v[36:37], v5, s[40:41]
	global_load_dwordx2 v[38:39], v5, s[40:41] offset:64
	global_load_dwordx2 v[40:41], v5, s[42:43]
	global_load_dwordx2 v[42:43], v5, s[42:43] offset:64
	global_load_dword v44, v6, s[46:47]
	global_load_dword v45, v9, s[44:45]
	v_add_u32_e32 v5, s54, v5
	v_add_u32_e32 v6, s55, v6
	v_add_u32_e32 v9, s54, v9
	s_sub_u32 s65, s6, 1
	ds_read_b128 v[148:151], v144
	s_waitcnt lgkmcnt(0)
	v_min_u32_e32 v148, v148, v149
	v_min3_u32 v148, v148, v150, v151
	s_nop 1
	v_readfirstlane_b32 s68, v148
	s_cmp_ge_u32 s68, s65
	s_cbranch_scc1 .Lsc_G_gom0
	s_mov_b32 s69, 0x100000
.Lsc_G_pollm0:
	s_sleep 12
	ds_read_b128 v[148:151], v144
	s_waitcnt lgkmcnt(0)
	v_min_u32_e32 v148, v148, v149
	v_min3_u32 v148, v148, v150, v151
	s_sub_u32 s69, s69, 1
	s_nop 1
	v_readfirstlane_b32 s68, v148
	s_cmp_eq_u32 s69, 0
	s_cbranch_scc1 .Lsc_G_gom0
	s_cmp_lt_u32 s68, s65
	s_cbranch_scc1 .Lsc_G_pollm0
.Lsc_G_gom0:
	ds_write_b32 v159, v161 offset:0
	ds_write_b128 v8, v[72:75] offset:0
	ds_write_b128 v8, v[76:79] offset:128
	ds_write_b128 v8, v[80:83] offset:256
	ds_write_b128 v8, v[84:87] offset:384
	ds_write2_b32 v138, v96, v97 offset0:1 offset1:3
	ds_write2_b32 v139, v88, v89 offset0:0 offset1:2
	ds_write2_b32 v138, v98, v99 offset0:65 offset1:67
	ds_write2_b32 v139, v90, v91 offset0:64 offset1:66
	ds_write2_b32 v138, v100, v101 offset0:33 offset1:35
	ds_write2_b32 v139, v92, v93 offset0:32 offset1:34
	ds_write2_b32 v138, v102, v103 offset0:97 offset1:99
	ds_write2_b32 v139, v94, v95 offset0:96 offset1:98
	ds_write2_b32 v142, v104, v105 offset1:36
	s_and_saveexec_b64 s[68:69], s[12:13]
	ds_write_b128 v158, v[88:91] offset:0
	ds_write_b128 v158, v[92:95] offset:128
	s_mov_b64 exec, s[68:69]
	ds_read_b128 v[120:123], v11 offset:0
	ds_read_b128 v[124:127], v11 offset:16
	ds_read_b128 v[128:131], v11 offset:32
	ds_read_b128 v[132:135], v11 offset:48
	s_waitcnt lgkmcnt(0)
	v_pk_add_f32 v[120:121], v[120:121], v[122:123]
	v_pk_add_f32 v[124:125], v[124:125], v[126:127]
	v_pk_add_f32 v[120:121], v[120:121], v[124:125]
	v_add_f32_e32 v136, v120, v121
	v_pk_add_f32 v[128:129], v[128:129], v[130:131]
	v_pk_add_f32 v[132:133], v[132:133], v[134:135]
	v_pk_add_f32 v[128:129], v[128:129], v[132:133]
	v_add_f32_e32 v137, v128, v129
	global_store_dwordx2 v7, v[136:137], s[48:49]
	v_add_u32_e32 v7, s64, v7
	s_add_i32 s6, s6, 1
	v_add_u32_e32 v146, 1, v146
	s_waitcnt lgkmcnt(0)
	ds_write_b32 v145, v146
	s_waitcnt vmcnt(10)
	v_lshlrev_b32_e32 v64, 16, v54
	v_and_b32_e32 v65, 0xffff0000, v54
	v_mul_f32_e32 v64, 0x3fb8aa3b, v64
	v_mul_f32_e32 v65, 0x3fb8aa3b, v65
	v_lshlrev_b32_e32 v66, 16, v55
	v_and_b32_e32 v67, 0xffff0000, v55
	v_mul_f32_e32 v66, 0x3fb8aa3b, v66
	v_mul_f32_e32 v67, 0x3fb8aa3b, v67
	v_lshlrev_b32_e32 v68, 16, v56
	v_and_b32_e32 v69, 0xffff0000, v56
	v_mul_f32_e32 v68, 0x3fb8aa3b, v68
	v_mul_f32_e32 v69, 0x3fb8aa3b, v69
	v_lshlrev_b32_e32 v70, 16, v57
	v_and_b32_e32 v71, 0xffff0000, v57
	v_mul_f32_e32 v70, 0x3fb8aa3b, v70
	v_mul_f32_e32 v71, 0x3fb8aa3b, v71
	ds_write_b128 v153, v[64:67]
	ds_write_b128 v153, v[68:71] offset:128
	s_waitcnt lgkmcnt(0)
	ds_read_b32 v124, v154 offset:0
	ds_read_b32 v125, v154 offset:256
	ds_read_b32 v126, v154 offset:512
	ds_read_b32 v127, v154 offset:768
	ds_read_b32 v128, v154 offset:1024
	ds_read_b32 v129, v154 offset:1280
	ds_read_b32 v130, v154 offset:1536
	ds_read_b32 v131, v154 offset:1792
	v_lshlrev_b32_e32 v108, 16, v50
	v_and_b32_e32 v109, 0xffff0000, v50
	v_lshlrev_b32_e32 v110, 16, v58
	v_and_b32_e32 v111, 0xffff0000, v58
	v_lshlrev_b32_e32 v96, 16, v46
	v_and_b32_e32 v97, 0xffff0000, v46
	v_pk_add_f32 v[112:113], v[110:111], -1.0 op_sel_hi:[1,0]
	v_pk_mul_f32 v[114:115], v[12:13], v[108:109]
	v_pk_fma_f32 v[112:113], v[20:21], v[112:113], 1.0 op_sel_hi:[1,1,0]
	v_pk_mul_f32 v[88:89], v[62:63], v[114:115] op_sel_hi:[0,1]
	v_pk_mul_f32 v[72:73], v[112:113], v[108:109]
	v_pk_mul_f32 v[80:81], v[88:89], v[110:111]
	v_lshlrev_b32_e32 v108, 16, v51
	v_and_b32_e32 v109, 0xffff0000, v51
	v_lshlrev_b32_e32 v110, 16, v59
	v_and_b32_e32 v111, 0xffff0000, v59
	v_lshlrev_b32_e32 v98, 16, v47
	v_and_b32_e32 v99, 0xffff0000, v47
	v_pk_add_f32 v[112:113], v[110:111], -1.0 op_sel_hi:[1,0]
	v_pk_mul_f32 v[114:115], v[14:15], v[108:109]
	v_pk_fma_f32 v[112:113], v[22:23], v[112:113], 1.0 op_sel_hi:[1,1,0]
	v_pk_mul_f32 v[90:91], v[62:63], v[114:115] op_sel_hi:[0,1]
	v_pk_mul_f32 v[74:75], v[112:113], v[108:109]
	v_pk_mul_f32 v[82:83], v[90:91], v[110:111]
	v_lshlrev_b32_e32 v108, 16, v52
	v_and_b32_e32 v109, 0xffff0000, v52
	v_lshlrev_b32_e32 v110, 16, v60
	v_and_b32_e32 v111, 0xffff0000, v60
	v_lshlrev_b32_e32 v100, 16, v48
	v_and_b32_e32 v101, 0xffff0000, v48
	v_pk_add_f32 v[112:113], v[110:111], -1.0 op_sel_hi:[1,0]
	v_pk_mul_f32 v[114:115], v[16:17], v[108:109]
	v_pk_fma_f32 v[112:113], v[24:25], v[112:113], 1.0 op_sel_hi:[1,1,0]
	v_pk_mul_f32 v[92:93], v[62:63], v[114:115] op_sel_hi:[0,1]
	v_pk_mul_f32 v[76:77], v[112:113], v[108:109]
	v_pk_mul_f32 v[84:85], v[92:93], v[110:111]
	v_lshlrev_b32_e32 v108, 16, v53
	v_and_b32_e32 v109, 0xffff0000, v53
	v_lshlrev_b32_e32 v110, 16, v61
	v_and_b32_e32 v111, 0xffff0000, v61
	v_lshlrev_b32_e32 v102, 16, v49
	v_and_b32_e32 v103, 0xffff0000, v49
	v_pk_add_f32 v[112:113], v[110:111], -1.0 op_sel_hi:[1,0]
	v_pk_mul_f32 v[114:115], v[18:19], v[108:109]
	v_pk_fma_f32 v[112:113], v[26:27], v[112:113], 1.0 op_sel_hi:[1,1,0]
	v_pk_mul_f32 v[94:95], v[62:63], v[114:115] op_sel_hi:[0,1]
	v_pk_mul_f32 v[78:79], v[112:113], v[108:109]
	v_pk_mul_f32 v[86:87], v[94:95], v[110:111]
	v_lshlrev_b32_e32 v104, 16, v63
	v_and_b32_e32 v105, 0xffff0000, v63
	s_waitcnt lgkmcnt(0)
	v_add_f32_e32 v125, v124, v125
	v_add_f32_e32 v126, v125, v126
	v_add_f32_e32 v127, v126, v127
	v_add_f32_e32 v128, v127, v128
	v_add_f32_e32 v129, v128, v129
	v_add_f32_e32 v130, v129, v130
	v_add_f32_e32 v131, v130, v131
	v_exp_f32_e64 v124, -v124
	v_exp_f32_e64 v125, -v125
	v_exp_f32_e64 v126, -v126
	v_exp_f32_e64 v127, -v127
	v_exp_f32_e64 v128, -v128
	v_exp_f32_e64 v129, -v129
	v_exp_f32_e64 v130, -v130
	v_exp_f32_e64 v131, -v131
	s_nop 0
	ds_write_b32 v155, v124 offset:256
	ds_write_b32 v155, v125 offset:512
	ds_write_b32 v155, v126 offset:768
	ds_write_b32 v155, v127 offset:1024
	ds_write_b32 v155, v128 offset:1280
	ds_write_b32 v155, v129 offset:1536
	ds_write_b32 v155, v130 offset:1792
	ds_write_b32 v155, v131 offset:2048
	v_mov_b32_e32 v161, v131
	s_waitcnt lgkmcnt(0)
	ds_read_b128 v[64:67], v153 offset:2048
	ds_read_b128 v[68:71], v153 offset:2176
	ds_read_b128 v[116:119], v153 offset:2304
	ds_read_b128 v[120:123], v153 offset:2432
	s_waitcnt lgkmcnt(0)
	v_rcp_f32_e32 v124, v116
	v_rcp_f32_e32 v125, v117
	v_rcp_f32_e32 v126, v118
	v_rcp_f32_e32 v127, v119
	v_rcp_f32_e32 v128, v120
	v_rcp_f32_e32 v129, v121
	v_rcp_f32_e32 v130, v122
	v_rcp_f32_e32 v131, v123
	s_nop 1
	v_pk_mul_f32 v[72:73], v[72:73], v[124:125]
	v_pk_mul_f32 v[80:81], v[80:81], v[124:125]
	v_pk_mul_f32 v[88:89], v[88:89], v[64:65]
	v_pk_mul_f32 v[96:97], v[96:97], v[116:117]
	v_pk_mul_f32 v[74:75], v[74:75], v[126:127]
	v_pk_mul_f32 v[82:83], v[82:83], v[126:127]
	v_pk_mul_f32 v[90:91], v[90:91], v[66:67]
	v_pk_mul_f32 v[98:99], v[98:99], v[118:119]
	v_pk_mul_f32 v[76:77], v[76:77], v[128:129]
	v_pk_mul_f32 v[84:85], v[84:85], v[128:129]
	v_pk_mul_f32 v[92:93], v[92:93], v[68:69]
	v_pk_mul_f32 v[100:101], v[100:101], v[120:121]
	v_pk_mul_f32 v[78:79], v[78:79], v[130:131]
	v_pk_mul_f32 v[86:87], v[86:87], v[130:131]
	v_pk_mul_f32 v[94:95], v[94:95], v[70:71]
	v_pk_mul_f32 v[102:103], v[102:103], v[122:123]
	global_load_dwordx2 v[46:47], v5, s[36:37]
	global_load_dwordx2 v[48:49], v5, s[36:37] offset:64
	global_load_dwordx2 v[50:51], v5, s[38:39]
	global_load_dwordx2 v[52:53], v5, s[38:39] offset:64
	global_load_dwordx2 v[54:55], v5, s[40:41]
	global_load_dwordx2 v[56:57], v5, s[40:41] offset:64
	global_load_dwordx2 v[58:59], v5, s[42:43]
	global_load_dwordx2 v[60:61], v5, s[42:43] offset:64
	global_load_dword v62, v6, s[46:47]
	global_load_dword v63, v9, s[44:45]
	v_add_u32_e32 v5, s54, v5
	v_add_u32_e32 v6, s55, v6
	v_add_u32_e32 v9, s54, v9
	s_sub_u32 s65, s6, 1
	ds_read_b128 v[148:151], v144
	s_waitcnt lgkmcnt(0)
	v_min_u32_e32 v148, v148, v149
	v_min3_u32 v148, v148, v150, v151
	s_nop 1
	v_readfirstlane_b32 s68, v148
	s_cmp_ge_u32 s68, s65
	s_cbranch_scc1 .Lsc_G_gom1
	s_mov_b32 s69, 0x100000

.Lsc_G_gom1:
	ds_write_b32 v159, v161 offset:34816
	ds_write_b128 v8, v[72:75] offset:34816
	ds_write_b128 v8, v[76:79] offset:34944
	ds_write_b128 v8, v[80:83] offset:35072
	ds_write_b128 v8, v[84:87] offset:35200
	ds_write2_b32 v140, v96, v97 offset0:1 offset1:3
	ds_write2_b32 v141, v88, v89 offset0:0 offset1:2
	ds_write2_b32 v140, v98, v99 offset0:65 offset1:67
	ds_write2_b32 v141, v90, v91 offset0:64 offset1:66
	ds_write2_b32 v140, v100, v101 offset0:33 offset1:35
	ds_write2_b32 v141, v92, v93 offset0:32 offset1:34
	ds_write2_b32 v140, v102, v103 offset0:97 offset1:99
	ds_write2_b32 v141, v94, v95 offset0:96 offset1:98
	ds_write2_b32 v143, v104, v105 offset1:36
	s_and_saveexec_b64 s[68:69], s[12:13]
	ds_write_b128 v158, v[88:91] offset:34816
	ds_write_b128 v158, v[92:95] offset:34944
	s_mov_b64 exec, s[68:69]
	ds_read_b128 v[120:123], v11 offset:16384
	ds_read_b128 v[124:127], v11 offset:16400
	ds_read_b128 v[128:131], v11 offset:16416
	ds_read_b128 v[132:135], v11 offset:16432
	s_waitcnt lgkmcnt(0)
	v_pk_add_f32 v[120:121], v[120:121], v[122:123]
	v_pk_add_f32 v[124:125], v[124:125], v[126:127]
	v_pk_add_f32 v[120:121], v[120:121], v[124:125]
	v_add_f32_e32 v136, v120, v121
	v_pk_add_f32 v[128:129], v[128:129], v[130:131]
	v_pk_add_f32 v[132:133], v[132:133], v[134:135]
	v_pk_add_f32 v[128:129], v[128:129], v[132:133]
	v_add_f32_e32 v137, v128, v129
	global_store_dwordx2 v7, v[136:137], s[48:49]
	v_add_u32_e32 v7, s64, v7
	s_add_i32 s6, s6, 1
	v_add_u32_e32 v146, 1, v146
	s_waitcnt lgkmcnt(0)
	ds_write_b32 v145, v146
	s_cmp_lt_u32 s6, 0xfe
	s_cbranch_scc1 .Lsc_G_loop
	s_waitcnt vmcnt(10)
	v_lshlrev_b32_e32 v64, 16, v36
	v_and_b32_e32 v65, 0xffff0000, v36
	v_mul_f32_e32 v64, 0x3fb8aa3b, v64
	v_mul_f32_e32 v65, 0x3fb8aa3b, v65
	v_lshlrev_b32_e32 v66, 16, v37
	v_and_b32_e32 v67, 0xffff0000, v37
	v_mul_f32_e32 v66, 0x3fb8aa3b, v66
	v_mul_f32_e32 v67, 0x3fb8aa3b, v67
	v_lshlrev_b32_e32 v68, 16, v38
	v_and_b32_e32 v69, 0xffff0000, v38
	v_mul_f32_e32 v68, 0x3fb8aa3b, v68
	v_mul_f32_e32 v69, 0x3fb8aa3b, v69
	v_lshlrev_b32_e32 v70, 16, v39
	v_and_b32_e32 v71, 0xffff0000, v39
	v_mul_f32_e32 v70, 0x3fb8aa3b, v70
	v_mul_f32_e32 v71, 0x3fb8aa3b, v71
	ds_write_b128 v153, v[64:67]
	ds_write_b128 v153, v[68:71] offset:128
	s_waitcnt lgkmcnt(0)
	ds_read_b32 v124, v154 offset:0
	ds_read_b32 v125, v154 offset:256
	ds_read_b32 v126, v154 offset:512
	ds_read_b32 v127, v154 offset:768
	ds_read_b32 v128, v154 offset:1024
	ds_read_b32 v129, v154 offset:1280
	ds_read_b32 v130, v154 offset:1536
	ds_read_b32 v131, v154 offset:1792
	v_lshlrev_b32_e32 v108, 16, v32
	v_and_b32_e32 v109, 0xffff0000, v32
	v_lshlrev_b32_e32 v110, 16, v40
	v_and_b32_e32 v111, 0xffff0000, v40
	v_lshlrev_b32_e32 v96, 16, v28
	v_and_b32_e32 v97, 0xffff0000, v28
	v_pk_add_f32 v[112:113], v[110:111], -1.0 op_sel_hi:[1,0]
	v_pk_mul_f32 v[114:115], v[12:13], v[108:109]
	v_pk_fma_f32 v[112:113], v[20:21], v[112:113], 1.0 op_sel_hi:[1,1,0]
	v_pk_mul_f32 v[88:89], v[44:45], v[114:115] op_sel_hi:[0,1]
	v_pk_mul_f32 v[72:73], v[112:113], v[108:109]
	v_pk_mul_f32 v[80:81], v[88:89], v[110:111]
	v_lshlrev_b32_e32 v108, 16, v33
	v_and_b32_e32 v109, 0xffff0000, v33
	v_lshlrev_b32_e32 v110, 16, v41
	v_and_b32_e32 v111, 0xffff0000, v41
	v_lshlrev_b32_e32 v98, 16, v29
	v_and_b32_e32 v99, 0xffff0000, v29
	v_pk_add_f32 v[112:113], v[110:111], -1.0 op_sel_hi:[1,0]
	v_pk_mul_f32 v[114:115], v[14:15], v[108:109]
	v_pk_fma_f32 v[112:113], v[22:23], v[112:113], 1.0 op_sel_hi:[1,1,0]
	v_pk_mul_f32 v[90:91], v[44:45], v[114:115] op_sel_hi:[0,1]
	v_pk_mul_f32 v[74:75], v[112:113], v[108:109]
	v_pk_mul_f32 v[82:83], v[90:91], v[110:111]
	v_lshlrev_b32_e32 v108, 16, v34
	v_and_b32_e32 v109, 0xffff0000, v34
	v_lshlrev_b32_e32 v110, 16, v42
	v_and_b32_e32 v111, 0xffff0000, v42
	v_lshlrev_b32_e32 v100, 16, v30
	v_and_b32_e32 v101, 0xffff0000, v30
	v_pk_add_f32 v[112:113], v[110:111], -1.0 op_sel_hi:[1,0]
	v_pk_mul_f32 v[114:115], v[16:17], v[108:109]
	v_pk_fma_f32 v[112:113], v[24:25], v[112:113], 1.0 op_sel_hi:[1,1,0]
	v_pk_mul_f32 v[92:93], v[44:45], v[114:115] op_sel_hi:[0,1]
	v_pk_mul_f32 v[76:77], v[112:113], v[108:109]
	v_pk_mul_f32 v[84:85], v[92:93], v[110:111]
	v_lshlrev_b32_e32 v108, 16, v35
	v_and_b32_e32 v109, 0xffff0000, v35
	v_lshlrev_b32_e32 v110, 16, v43
	v_and_b32_e32 v111, 0xffff0000, v43
	v_lshlrev_b32_e32 v102, 16, v31
	v_and_b32_e32 v103, 0xffff0000, v31
	v_pk_add_f32 v[112:113], v[110:111], -1.0 op_sel_hi:[1,0]
	v_pk_mul_f32 v[114:115], v[18:19], v[108:109]
	v_pk_fma_f32 v[112:113], v[26:27], v[112:113], 1.0 op_sel_hi:[1,1,0]
	v_pk_mul_f32 v[94:95], v[44:45], v[114:115] op_sel_hi:[0,1]
	v_pk_mul_f32 v[78:79], v[112:113], v[108:109]
	v_pk_mul_f32 v[86:87], v[94:95], v[110:111]
	v_lshlrev_b32_e32 v104, 16, v45
	v_and_b32_e32 v105, 0xffff0000, v45
	s_waitcnt lgkmcnt(0)
	v_add_f32_e32 v125, v124, v125
	v_add_f32_e32 v126, v125, v126
	v_add_f32_e32 v127, v126, v127
	v_add_f32_e32 v128, v127, v128
	v_add_f32_e32 v129, v128, v129
	v_add_f32_e32 v130, v129, v130
	v_add_f32_e32 v131, v130, v131
	v_exp_f32_e64 v124, -v124
	v_exp_f32_e64 v125, -v125
	v_exp_f32_e64 v126, -v126
	v_exp_f32_e64 v127, -v127
	v_exp_f32_e64 v128, -v128
	v_exp_f32_e64 v129, -v129
	v_exp_f32_e64 v130, -v130
	v_exp_f32_e64 v131, -v131
	s_nop 0
	ds_write_b32 v155, v124 offset:256
	ds_write_b32 v155, v125 offset:512
	ds_write_b32 v155, v126 offset:768
	ds_write_b32 v155, v127 offset:1024
	ds_write_b32 v155, v128 offset:1280
	ds_write_b32 v155, v129 offset:1536
	ds_write_b32 v155, v130 offset:1792
	ds_write_b32 v155, v131 offset:2048
	v_mov_b32_e32 v161, v131
	s_waitcnt lgkmcnt(0)
	ds_read_b128 v[64:67], v153 offset:2048
	ds_read_b128 v[68:71], v153 offset:2176
	ds_read_b128 v[116:119], v153 offset:2304
	ds_read_b128 v[120:123], v153 offset:2432
	s_waitcnt lgkmcnt(0)
	v_rcp_f32_e32 v124, v116
	v_rcp_f32_e32 v125, v117
	v_rcp_f32_e32 v126, v118
	v_rcp_f32_e32 v127, v119
	v_rcp_f32_e32 v128, v120
	v_rcp_f32_e32 v129, v121
	v_rcp_f32_e32 v130, v122
	v_rcp_f32_e32 v131, v123
	s_nop 1
	v_pk_mul_f32 v[72:73], v[72:73], v[124:125]
	v_pk_mul_f32 v[80:81], v[80:81], v[124:125]
	v_pk_mul_f32 v[88:89], v[88:89], v[64:65]
	v_pk_mul_f32 v[96:97], v[96:97], v[116:117]
	v_pk_mul_f32 v[74:75], v[74:75], v[126:127]
	v_pk_mul_f32 v[82:83], v[82:83], v[126:127]
	v_pk_mul_f32 v[90:91], v[90:91], v[66:67]
	v_pk_mul_f32 v[98:99], v[98:99], v[118:119]
	v_pk_mul_f32 v[76:77], v[76:77], v[128:129]
	v_pk_mul_f32 v[84:85], v[84:85], v[128:129]
	v_pk_mul_f32 v[92:93], v[92:93], v[68:69]
	v_pk_mul_f32 v[100:101], v[100:101], v[120:121]
	v_pk_mul_f32 v[78:79], v[78:79], v[130:131]
	v_pk_mul_f32 v[86:87], v[86:87], v[130:131]
	v_pk_mul_f32 v[94:95], v[94:95], v[70:71]
	v_pk_mul_f32 v[102:103], v[102:103], v[122:123]
	s_sub_u32 s65, s6, 1
	ds_read_b128 v[148:151], v144
	s_waitcnt lgkmcnt(0)
	v_min_u32_e32 v148, v148, v149
	v_min3_u32 v148, v148, v150, v151
	s_nop 1
	v_readfirstlane_b32 s68, v148
	s_cmp_ge_u32 s68, s65
	s_cbranch_scc1 .Lsc_G_goz0
	s_mov_b32 s69, 0x100000

.Lsc_G_goz0:
	ds_write_b32 v159, v161 offset:0
	ds_write_b128 v8, v[72:75] offset:0
	ds_write_b128 v8, v[76:79] offset:128
	ds_write_b128 v8, v[80:83] offset:256
	ds_write_b128 v8, v[84:87] offset:384
	ds_write2_b32 v138, v96, v97 offset0:1 offset1:3
	ds_write2_b32 v139, v88, v89 offset0:0 offset1:2
	ds_write2_b32 v138, v98, v99 offset0:65 offset1:67
	ds_write2_b32 v139, v90, v91 offset0:64 offset1:66
	ds_write2_b32 v138, v100, v101 offset0:33 offset1:35
	ds_write2_b32 v139, v92, v93 offset0:32 offset1:34
	ds_write2_b32 v138, v102, v103 offset0:97 offset1:99
	ds_write2_b32 v139, v94, v95 offset0:96 offset1:98
	ds_write2_b32 v142, v104, v105 offset1:36
	s_and_saveexec_b64 s[68:69], s[12:13]
	ds_write_b128 v158, v[88:91] offset:0
	ds_write_b128 v158, v[92:95] offset:128
	s_mov_b64 exec, s[68:69]
	ds_read_b128 v[120:123], v11 offset:0
	ds_read_b128 v[124:127], v11 offset:16
	ds_read_b128 v[128:131], v11 offset:32
	ds_read_b128 v[132:135], v11 offset:48
	s_waitcnt lgkmcnt(0)
	v_pk_add_f32 v[120:121], v[120:121], v[122:123]
	v_pk_add_f32 v[124:125], v[124:125], v[126:127]
	v_pk_add_f32 v[120:121], v[120:121], v[124:125]
	v_add_f32_e32 v136, v120, v121
	v_pk_add_f32 v[128:129], v[128:129], v[130:131]
	v_pk_add_f32 v[132:133], v[132:133], v[134:135]
	v_pk_add_f32 v[128:129], v[128:129], v[132:133]
	v_add_f32_e32 v137, v128, v129
	global_store_dwordx2 v7, v[136:137], s[48:49]
	v_add_u32_e32 v7, s64, v7
	s_add_i32 s6, s6, 1
	v_add_u32_e32 v146, 1, v146
	s_waitcnt lgkmcnt(0)
	ds_write_b32 v145, v146
	s_waitcnt vmcnt(0)
	v_lshlrev_b32_e32 v64, 16, v54
	v_and_b32_e32 v65, 0xffff0000, v54
	v_mul_f32_e32 v64, 0x3fb8aa3b, v64
	v_mul_f32_e32 v65, 0x3fb8aa3b, v65
	v_lshlrev_b32_e32 v66, 16, v55
	v_and_b32_e32 v67, 0xffff0000, v55
	v_mul_f32_e32 v66, 0x3fb8aa3b, v66
	v_mul_f32_e32 v67, 0x3fb8aa3b, v67
	v_lshlrev_b32_e32 v68, 16, v56
	v_and_b32_e32 v69, 0xffff0000, v56
	v_mul_f32_e32 v68, 0x3fb8aa3b, v68
	v_mul_f32_e32 v69, 0x3fb8aa3b, v69
	v_lshlrev_b32_e32 v70, 16, v57
	v_and_b32_e32 v71, 0xffff0000, v57
	v_mul_f32_e32 v70, 0x3fb8aa3b, v70
	v_mul_f32_e32 v71, 0x3fb8aa3b, v71
	ds_write_b128 v153, v[64:67]
	ds_write_b128 v153, v[68:71] offset:128
	s_waitcnt lgkmcnt(0)
	ds_read_b32 v124, v154 offset:0
	ds_read_b32 v125, v154 offset:256
	ds_read_b32 v126, v154 offset:512
	ds_read_b32 v127, v154 offset:768
	ds_read_b32 v128, v154 offset:1024
	ds_read_b32 v129, v154 offset:1280
	ds_read_b32 v130, v154 offset:1536
	ds_read_b32 v131, v154 offset:1792
	v_lshlrev_b32_e32 v108, 16, v50
	v_and_b32_e32 v109, 0xffff0000, v50
	v_lshlrev_b32_e32 v110, 16, v58
	v_and_b32_e32 v111, 0xffff0000, v58
	v_lshlrev_b32_e32 v96, 16, v46
	v_and_b32_e32 v97, 0xffff0000, v46
	v_pk_add_f32 v[112:113], v[110:111], -1.0 op_sel_hi:[1,0]
	v_pk_mul_f32 v[114:115], v[12:13], v[108:109]
	v_pk_fma_f32 v[112:113], v[20:21], v[112:113], 1.0 op_sel_hi:[1,1,0]
	v_pk_mul_f32 v[88:89], v[62:63], v[114:115] op_sel_hi:[0,1]
	v_pk_mul_f32 v[72:73], v[112:113], v[108:109]
	v_pk_mul_f32 v[80:81], v[88:89], v[110:111]
	v_lshlrev_b32_e32 v108, 16, v51
	v_and_b32_e32 v109, 0xffff0000, v51
	v_lshlrev_b32_e32 v110, 16, v59
	v_and_b32_e32 v111, 0xffff0000, v59
	v_lshlrev_b32_e32 v98, 16, v47
	v_and_b32_e32 v99, 0xffff0000, v47
	v_pk_add_f32 v[112:113], v[110:111], -1.0 op_sel_hi:[1,0]
	v_pk_mul_f32 v[114:115], v[14:15], v[108:109]
	v_pk_fma_f32 v[112:113], v[22:23], v[112:113], 1.0 op_sel_hi:[1,1,0]
	v_pk_mul_f32 v[90:91], v[62:63], v[114:115] op_sel_hi:[0,1]
	v_pk_mul_f32 v[74:75], v[112:113], v[108:109]
	v_pk_mul_f32 v[82:83], v[90:91], v[110:111]
	v_lshlrev_b32_e32 v108, 16, v52
	v_and_b32_e32 v109, 0xffff0000, v52
	v_lshlrev_b32_e32 v110, 16, v60
	v_and_b32_e32 v111, 0xffff0000, v60
	v_lshlrev_b32_e32 v100, 16, v48
	v_and_b32_e32 v101, 0xffff0000, v48
	v_pk_add_f32 v[112:113], v[110:111], -1.0 op_sel_hi:[1,0]
	v_pk_mul_f32 v[114:115], v[16:17], v[108:109]
	v_pk_fma_f32 v[112:113], v[24:25], v[112:113], 1.0 op_sel_hi:[1,1,0]
	v_pk_mul_f32 v[92:93], v[62:63], v[114:115] op_sel_hi:[0,1]
	v_pk_mul_f32 v[76:77], v[112:113], v[108:109]
	v_pk_mul_f32 v[84:85], v[92:93], v[110:111]
	v_lshlrev_b32_e32 v108, 16, v53
	v_and_b32_e32 v109, 0xffff0000, v53
	v_lshlrev_b32_e32 v110, 16, v61
	v_and_b32_e32 v111, 0xffff0000, v61
	v_lshlrev_b32_e32 v102, 16, v49
	v_and_b32_e32 v103, 0xffff0000, v49
	v_pk_add_f32 v[112:113], v[110:111], -1.0 op_sel_hi:[1,0]
	v_pk_mul_f32 v[114:115], v[18:19], v[108:109]
	v_pk_fma_f32 v[112:113], v[26:27], v[112:113], 1.0 op_sel_hi:[1,1,0]
	v_pk_mul_f32 v[94:95], v[62:63], v[114:115] op_sel_hi:[0,1]
	v_pk_mul_f32 v[78:79], v[112:113], v[108:109]
	v_pk_mul_f32 v[86:87], v[94:95], v[110:111]
	v_lshlrev_b32_e32 v104, 16, v63
	v_and_b32_e32 v105, 0xffff0000, v63
	s_waitcnt lgkmcnt(0)
	v_add_f32_e32 v125, v124, v125
	v_add_f32_e32 v126, v125, v126
	v_add_f32_e32 v127, v126, v127
	v_add_f32_e32 v128, v127, v128
	v_add_f32_e32 v129, v128, v129
	v_add_f32_e32 v130, v129, v130
	v_add_f32_e32 v131, v130, v131
	v_exp_f32_e64 v124, -v124
	v_exp_f32_e64 v125, -v125
	v_exp_f32_e64 v126, -v126
	v_exp_f32_e64 v127, -v127
	v_exp_f32_e64 v128, -v128
	v_exp_f32_e64 v129, -v129
	v_exp_f32_e64 v130, -v130
	v_exp_f32_e64 v131, -v131
	s_nop 0
	ds_write_b32 v155, v124 offset:256
	ds_write_b32 v155, v125 offset:512
	ds_write_b32 v155, v126 offset:768
	ds_write_b32 v155, v127 offset:1024
	ds_write_b32 v155, v128 offset:1280
	ds_write_b32 v155, v129 offset:1536
	ds_write_b32 v155, v130 offset:1792
	ds_write_b32 v155, v131 offset:2048
	v_mov_b32_e32 v161, v131
	s_waitcnt lgkmcnt(0)
	ds_read_b128 v[64:67], v153 offset:2048
	ds_read_b128 v[68:71], v153 offset:2176
	ds_read_b128 v[116:119], v153 offset:2304
	ds_read_b128 v[120:123], v153 offset:2432
	s_waitcnt lgkmcnt(0)
	v_rcp_f32_e32 v124, v116
	v_rcp_f32_e32 v125, v117
	v_rcp_f32_e32 v126, v118
	v_rcp_f32_e32 v127, v119
	v_rcp_f32_e32 v128, v120
	v_rcp_f32_e32 v129, v121
	v_rcp_f32_e32 v130, v122
	v_rcp_f32_e32 v131, v123
	s_nop 1
	v_pk_mul_f32 v[72:73], v[72:73], v[124:125]
	v_pk_mul_f32 v[80:81], v[80:81], v[124:125]
	v_pk_mul_f32 v[88:89], v[88:89], v[64:65]
	v_pk_mul_f32 v[96:97], v[96:97], v[116:117]
	v_pk_mul_f32 v[74:75], v[74:75], v[126:127]
	v_pk_mul_f32 v[82:83], v[82:83], v[126:127]
	v_pk_mul_f32 v[90:91], v[90:91], v[66:67]
	v_pk_mul_f32 v[98:99], v[98:99], v[118:119]
	v_pk_mul_f32 v[76:77], v[76:77], v[128:129]
	v_pk_mul_f32 v[84:85], v[84:85], v[128:129]
	v_pk_mul_f32 v[92:93], v[92:93], v[68:69]
	v_pk_mul_f32 v[100:101], v[100:101], v[120:121]
	v_pk_mul_f32 v[78:79], v[78:79], v[130:131]
	v_pk_mul_f32 v[86:87], v[86:87], v[130:131]
	v_pk_mul_f32 v[94:95], v[94:95], v[70:71]
	v_pk_mul_f32 v[102:103], v[102:103], v[122:123]
	s_sub_u32 s65, s6, 1
	ds_read_b128 v[148:151], v144
	s_waitcnt lgkmcnt(0)
	v_min_u32_e32 v148, v148, v149
	v_min3_u32 v148, v148, v150, v151
	s_nop 1
	v_readfirstlane_b32 s68, v148
	s_cmp_ge_u32 s68, s65
	s_cbranch_scc1 .Lsc_G_goz1
	s_mov_b32 s69, 0x100000

.Lsc_G_goz1:
	ds_write_b32 v159, v161 offset:34816
	ds_write_b128 v8, v[72:75] offset:34816
	ds_write_b128 v8, v[76:79] offset:34944
	ds_write_b128 v8, v[80:83] offset:35072
	ds_write_b128 v8, v[84:87] offset:35200
	ds_write2_b32 v140, v96, v97 offset0:1 offset1:3
	ds_write2_b32 v141, v88, v89 offset0:0 offset1:2
	ds_write2_b32 v140, v98, v99 offset0:65 offset1:67
	ds_write2_b32 v141, v90, v91 offset0:64 offset1:66
	ds_write2_b32 v140, v100, v101 offset0:33 offset1:35
	ds_write2_b32 v141, v92, v93 offset0:32 offset1:34
	ds_write2_b32 v140, v102, v103 offset0:97 offset1:99
	ds_write2_b32 v141, v94, v95 offset0:96 offset1:98
	ds_write2_b32 v143, v104, v105 offset1:36
	s_and_saveexec_b64 s[68:69], s[12:13]
	ds_write_b128 v158, v[88:91] offset:34816
	ds_write_b128 v158, v[92:95] offset:34944
	s_mov_b64 exec, s[68:69]
	ds_read_b128 v[120:123], v11 offset:16384
	ds_read_b128 v[124:127], v11 offset:16400
	ds_read_b128 v[128:131], v11 offset:16416
	ds_read_b128 v[132:135], v11 offset:16432
	s_waitcnt lgkmcnt(0)
	v_pk_add_f32 v[120:121], v[120:121], v[122:123]
	v_pk_add_f32 v[124:125], v[124:125], v[126:127]
	v_pk_add_f32 v[120:121], v[120:121], v[124:125]
	v_add_f32_e32 v136, v120, v121
	v_pk_add_f32 v[128:129], v[128:129], v[130:131]
	v_pk_add_f32 v[132:133], v[132:133], v[134:135]
	v_pk_add_f32 v[128:129], v[128:129], v[132:133]
	v_add_f32_e32 v137, v128, v129
	global_store_dwordx2 v7, v[136:137], s[48:49]
	v_add_u32_e32 v7, s64, v7
	s_add_i32 s6, s6, 1
	v_add_u32_e32 v146, 1, v146
	s_waitcnt lgkmcnt(0)
	ds_write_b32 v145, v146
	s_sub_u32 s65, s6, 1
	ds_read_b128 v[148:151], v144
	s_waitcnt lgkmcnt(0)
	v_min_u32_e32 v148, v148, v149
	v_min3_u32 v148, v148, v150, v151
	s_nop 1
	v_readfirstlane_b32 s68, v148
	s_cmp_ge_u32 s68, s65
	s_cbranch_scc1 .Lsc_G_goz2
	s_mov_b32 s69, 0x100000
